# hand-written RWKV consumer loop (prefetched LDS operands, batched y reduction) + RG-LRU moved to an 8-wave segmented pre-pass
# speedup vs baseline: 1.0230x; 1.0230x over previous
.LBB0_868:
	s_cmp_lt_i32 s88, 5
	s_cselect_b64 s[4:5], -1, 0
	s_and_b64 s[0:1], s[4:5], s[0:1]
	v_writelane_b32 v255, s0, 36
	s_andn2_b64 vcc, exec, s[0:1]
	s_nop 0
	v_writelane_b32 v255, s1, 37
	s_cbranch_vccnz .LBB0_922
	s_cmpk_gt_i32 s2, 0xff
	v_mbcnt_lo_u32_b32 v32, -1, 0
	v_mbcnt_hi_u32_b32 v32, -1, v32
	s_cbranch_scc1 .LBB0_921
	v_readlane_b32 s4, v255, 35
	s_cmpk_gt_u32 s4, 0xff
	s_cselect_b64 s[8:9], -1, 0
	s_add_u32 s10, s96, 0x37800000
	s_addc_u32 s11, s97, 0
	s_add_u32 s12, s96, 0x3b800000
	s_addc_u32 s13, s97, 0
	s_add_u32 s14, s96, 0x21800000
	s_addc_u32 s15, s97, 0
	s_add_u32 s16, s96, 0x25800000
	s_addc_u32 s17, s97, 0
	s_cmp_eq_u32 s33, 4
	s_mov_b64 s[18:19], 0
	s_add_i32 s3, s33, -4
	s_and_b32 s0, s3, 0x7ff
	s_cmp_eq_u32 s0, 0
	s_cselect_b64 s[22:23], -1, 0
	s_and_b64 s[0:1], s[22:23], exec
	s_cselect_b32 s27, 0, -1
	s_cselect_b32 s26, 0, 0xfffff200
	s_and_b32 s0, s4, 0x1ffc0
	s_cmp_eq_u32 s0, 0
	s_cselect_b64 s[28:29], -1, 0
	s_and_b64 s[0:1], s[28:29], exec
	s_cselect_b32 s31, 0, -1
	s_cselect_b32 s30, 0, 0xfffff200
	s_mul_i32 s70, s33, 0x600
	s_add_i32 s72, s33, 4
	s_add_i32 s71, s70, 0xffffe800
	s_and_b32 s0, s72, 0x7ff
	s_cmp_eq_u32 s0, 0
	s_cselect_b64 s[34:35], -1, 0
	s_add_i32 s74, s33, 8
	s_add_i32 s73, s70, 0x1800
	s_and_b32 s0, s74, 0x7ff
	s_cmp_eq_u32 s0, 0
	s_cselect_b64 s[38:39], -1, 0
	s_add_i32 s77, s33, 12
	s_add_i32 s76, s70, 0x3000
	s_and_b32 s0, s77, 0x7ff
	s_cmp_eq_u32 s0, 0
	s_cselect_b64 s[40:41], -1, 0
	s_add_i32 s78, s33, 16
	s_and_b32 s0, s78, 0x7ff
	s_cmp_eq_u32 s0, 0
	s_cselect_b64 s[42:43], -1, 0
	s_add_i32 s79, s33, 20
	s_and_b32 s0, s79, 0x7ff
	s_cmp_eq_u32 s0, 0
	s_cselect_b64 s[48:49], -1, 0
	s_add_i32 s80, s33, 24
	s_and_b32 s0, s80, 0x7ff
	v_ashrrev_i32_e32 v33, 31, v32
	s_cmp_eq_u32 s0, 0
	v_lshl_add_u64 v[0:1], v[32:33], 1, s[96:97]
	s_mov_b64 s[4:5], 0xf800000
	s_cselect_b64 s[50:51], -1, 0
	s_add_u32 s81, s96, 0x4100000
	v_lshl_add_u64 v[34:35], v[0:1], 0, s[4:5]
	s_mov_b64 s[4:5], 0x2b800000
	s_addc_u32 s82, s97, 0
	v_and_b32_e32 v2, 15, v32
	v_lshl_add_u64 v[36:37], v[0:1], 0, s[4:5]
	s_lshl_b32 s4, s33, 6
	v_lshlrev_b32_e32 v0, 1, v2
	s_add_i32 s4, s4, 0
	v_lshl_or_b32 v38, s33, 5, v0
	v_mov_b32_e32 v39, 0
	v_lshl_add_u32 v0, v2, 2, s4
	s_mov_b32 s21, 0
	s_movk_i32 s75, 0x3000
	v_lshl_add_u32 v56, v32, 2, 0
	v_cmp_eq_u32_e64 s[0:1], 0, v32
	v_lshl_add_u64 v[40:41], s[96:97], 0, v[38:39]
	s_lshl_b32 s83, s2, 8
	s_lshl_b32 s84, s92, 8
	v_add_u32_e32 v38, 0x500, v0
	v_cndmask_b32_e64 v57, 0, 1, s[18:19]
	s_mov_b32 s85, 0x5040100
	v_mov_b32_e32 v58, 0xe00
	v_mov_b32_e32 v59, 0xc00
	s_mov_b32 s90, s2
	s_mov_b32 s91, s2
	s_branch .LBB0_872

.LBB0_872:
	s_lshr_b32 s4, s91, 3
	s_and_b32 s5, s91, 7
	s_lshl_b32 s4, s4, 21
	s_lshl_b32 s5, s5, 7
	s_or_b32 s4, s4, s5
	s_lshl_b32 s5, s33, 18
	s_or_b32 s4, s4, s5
	v_lshl_add_u32 v0, v32, 1, s4
	v_add_u32_e32 v1, 0x1000, v0
	v_mov_b32_e32 v4, 0
	v_mov_b32_e32 v5, 1.0
	s_mov_b32 s6, 0
	global_load_ushort v60, v0, s[10:11] offset:0
	global_load_ushort v68, v0, s[12:13] offset:0
	global_load_ushort v61, v0, s[10:11] offset:1024
	global_load_ushort v69, v0, s[12:13] offset:1024
	global_load_ushort v62, v0, s[10:11] offset:2048
	global_load_ushort v70, v0, s[12:13] offset:2048
	global_load_ushort v63, v0, s[10:11] offset:3072
	global_load_ushort v71, v0, s[12:13] offset:3072
	global_load_ushort v64, v1, s[10:11] offset:0
	global_load_ushort v72, v1, s[12:13] offset:0
	global_load_ushort v65, v1, s[10:11] offset:1024
	global_load_ushort v73, v1, s[12:13] offset:1024
	global_load_ushort v66, v1, s[10:11] offset:2048
	global_load_ushort v74, v1, s[12:13] offset:2048
	global_load_ushort v67, v1, s[10:11] offset:3072
	global_load_ushort v75, v1, s[12:13] offset:3072
	v_add_u32_e32 v0, 0x2000, v0
	v_add_u32_e32 v1, 0x2000, v1
.Lrg_p1:
	global_load_ushort v84, v0, s[10:11] offset:0
	global_load_ushort v92, v0, s[12:13] offset:0
	global_load_ushort v85, v0, s[10:11] offset:1024
	global_load_ushort v93, v0, s[12:13] offset:1024
	global_load_ushort v86, v0, s[10:11] offset:2048
	global_load_ushort v94, v0, s[12:13] offset:2048
	global_load_ushort v87, v0, s[10:11] offset:3072
	global_load_ushort v95, v0, s[12:13] offset:3072
	global_load_ushort v88, v1, s[10:11] offset:0
	global_load_ushort v96, v1, s[12:13] offset:0
	global_load_ushort v89, v1, s[10:11] offset:1024
	global_load_ushort v97, v1, s[12:13] offset:1024
	global_load_ushort v90, v1, s[10:11] offset:2048
	global_load_ushort v98, v1, s[12:13] offset:2048
	global_load_ushort v91, v1, s[10:11] offset:3072
	global_load_ushort v99, v1, s[12:13] offset:3072
	v_add_u32_e32 v0, 0x2000, v0
	v_add_u32_e32 v1, 0x2000, v1
	s_waitcnt vmcnt(16)
	v_lshlrev_b32_e32 v8, 16, v60
	v_mul_f32_e32 v8, 0x3fb8aa3b, v8
	v_lshlrev_b32_e32 v9, 16, v61
	v_mul_f32_e32 v9, 0x3fb8aa3b, v9
	v_lshlrev_b32_e32 v10, 16, v62
	v_mul_f32_e32 v10, 0x3fb8aa3b, v10
	v_lshlrev_b32_e32 v11, 16, v63
	v_mul_f32_e32 v11, 0x3fb8aa3b, v11
	v_lshlrev_b32_e32 v12, 16, v64
	v_mul_f32_e32 v12, 0x3fb8aa3b, v12
	v_lshlrev_b32_e32 v13, 16, v65
	v_mul_f32_e32 v13, 0x3fb8aa3b, v13
	v_lshlrev_b32_e32 v14, 16, v66
	v_mul_f32_e32 v14, 0x3fb8aa3b, v14
	v_lshlrev_b32_e32 v15, 16, v67
	v_mul_f32_e32 v15, 0x3fb8aa3b, v15
	v_exp_f32_e32 v8, v8
	v_lshlrev_b32_e32 v16, 16, v68
	v_exp_f32_e32 v9, v9
	v_lshlrev_b32_e32 v17, 16, v69
	v_exp_f32_e32 v10, v10
	v_lshlrev_b32_e32 v18, 16, v70
	v_exp_f32_e32 v11, v11
	v_lshlrev_b32_e32 v19, 16, v71
	v_exp_f32_e32 v12, v12
	v_lshlrev_b32_e32 v20, 16, v72
	v_exp_f32_e32 v13, v13
	v_lshlrev_b32_e32 v21, 16, v73
	v_exp_f32_e32 v14, v14
	v_lshlrev_b32_e32 v22, 16, v74
	v_exp_f32_e32 v15, v15
	v_lshlrev_b32_e32 v23, 16, v75
	v_fma_f32 v4, v8, v4, v16
	v_mul_f32_e32 v5, v5, v8
	v_fma_f32 v4, v9, v4, v17
	v_mul_f32_e32 v5, v5, v9
	v_fma_f32 v4, v10, v4, v18
	v_mul_f32_e32 v5, v5, v10
	v_fma_f32 v4, v11, v4, v19
	v_mul_f32_e32 v5, v5, v11
	v_fma_f32 v4, v12, v4, v20
	v_mul_f32_e32 v5, v5, v12
	v_fma_f32 v4, v13, v4, v21
	v_mul_f32_e32 v5, v5, v13
	v_fma_f32 v4, v14, v4, v22
	v_mul_f32_e32 v5, v5, v14
	v_fma_f32 v4, v15, v4, v23
	v_mul_f32_e32 v5, v5, v15
	s_cmp_eq_u32 s6, 30
	s_cselect_b32 s7, 0xffffe000, 0
	v_add_u32_e32 v0, s7, v0
	v_add_u32_e32 v1, s7, v1
	global_load_ushort v60, v0, s[10:11] offset:0
	global_load_ushort v68, v0, s[12:13] offset:0
	global_load_ushort v61, v0, s[10:11] offset:1024
	global_load_ushort v69, v0, s[12:13] offset:1024
	global_load_ushort v62, v0, s[10:11] offset:2048
	global_load_ushort v70, v0, s[12:13] offset:2048
	global_load_ushort v63, v0, s[10:11] offset:3072
	global_load_ushort v71, v0, s[12:13] offset:3072
	global_load_ushort v64, v1, s[10:11] offset:0
	global_load_ushort v72, v1, s[12:13] offset:0
	global_load_ushort v65, v1, s[10:11] offset:1024
	global_load_ushort v73, v1, s[12:13] offset:1024
	global_load_ushort v66, v1, s[10:11] offset:2048
	global_load_ushort v74, v1, s[12:13] offset:2048
	global_load_ushort v67, v1, s[10:11] offset:3072
	global_load_ushort v75, v1, s[12:13] offset:3072
	v_add_u32_e32 v0, 0x2000, v0
	v_add_u32_e32 v1, 0x2000, v1
	s_waitcnt vmcnt(16)
	v_lshlrev_b32_e32 v8, 16, v84
	v_mul_f32_e32 v8, 0x3fb8aa3b, v8
	v_lshlrev_b32_e32 v9, 16, v85
	v_mul_f32_e32 v9, 0x3fb8aa3b, v9
	v_lshlrev_b32_e32 v10, 16, v86
	v_mul_f32_e32 v10, 0x3fb8aa3b, v10
	v_lshlrev_b32_e32 v11, 16, v87
	v_mul_f32_e32 v11, 0x3fb8aa3b, v11
	v_lshlrev_b32_e32 v12, 16, v88
	v_mul_f32_e32 v12, 0x3fb8aa3b, v12
	v_lshlrev_b32_e32 v13, 16, v89
	v_mul_f32_e32 v13, 0x3fb8aa3b, v13
	v_lshlrev_b32_e32 v14, 16, v90
	v_mul_f32_e32 v14, 0x3fb8aa3b, v14
	v_lshlrev_b32_e32 v15, 16, v91
	v_mul_f32_e32 v15, 0x3fb8aa3b, v15
	v_exp_f32_e32 v8, v8
	v_lshlrev_b32_e32 v16, 16, v92
	v_exp_f32_e32 v9, v9
	v_lshlrev_b32_e32 v17, 16, v93
	v_exp_f32_e32 v10, v10
	v_lshlrev_b32_e32 v18, 16, v94
	v_exp_f32_e32 v11, v11
	v_lshlrev_b32_e32 v19, 16, v95
	v_exp_f32_e32 v12, v12
	v_lshlrev_b32_e32 v20, 16, v96
	v_exp_f32_e32 v13, v13
	v_lshlrev_b32_e32 v21, 16, v97
	v_exp_f32_e32 v14, v14
	v_lshlrev_b32_e32 v22, 16, v98
	v_exp_f32_e32 v15, v15
	v_lshlrev_b32_e32 v23, 16, v99
	v_fma_f32 v4, v8, v4, v16
	v_mul_f32_e32 v5, v5, v8
	v_fma_f32 v4, v9, v4, v17
	v_mul_f32_e32 v5, v5, v9
	v_fma_f32 v4, v10, v4, v18
	v_mul_f32_e32 v5, v5, v10
	v_fma_f32 v4, v11, v4, v19
	v_mul_f32_e32 v5, v5, v11
	v_fma_f32 v4, v12, v4, v20
	v_mul_f32_e32 v5, v5, v12
	v_fma_f32 v4, v13, v4, v21
	v_mul_f32_e32 v5, v5, v13
	v_fma_f32 v4, v14, v4, v22
	v_mul_f32_e32 v5, v5, v14
	v_fma_f32 v4, v15, v4, v23
	v_mul_f32_e32 v5, v5, v15
	s_add_i32 s6, s6, 2
	s_cmp_lt_u32 s6, 32
	s_cbranch_scc1 .Lrg_p1
	s_waitcnt vmcnt(0)
	v_lshlrev_b32_e32 v6, 2, v32
	v_add_u32_e32 v6, 0x19000, v6
	s_lshl_b32 s5, s33, 8
	v_add_u32_e32 v7, s5, v6
	ds_write_b32 v7, v5
	ds_write_b32 v7, v4 offset:2048
	s_waitcnt lgkmcnt(0)
	s_barrier
	v_mov_b32_e32 v4, 0
	s_cmp_eq_u32 s33, 0
	s_cbranch_scc1 .Lrg_c_done
	s_mov_b32 s6, 0
.Lrg_c:
	ds_read_b32 v8, v6
	ds_read_b32 v9, v6 offset:2048
	v_add_u32_e32 v6, 0x100, v6
	s_add_i32 s6, s6, 1
	s_cmp_lt_u32 s6, s33
	s_waitcnt lgkmcnt(0)
	v_fma_f32 v4, v8, v4, v9
	s_cbranch_scc1 .Lrg_c
.Lrg_c_done:
	v_lshl_add_u32 v0, v32, 1, s4
	v_add_u32_e32 v1, 0x1000, v0
	v_mov_b32_e32 v2, v0
	v_mov_b32_e32 v3, v1
	v_mov_b32_e32 v7, 0
	v_mov_b32_e32 v50, 0xbdd2d3e8
	v_mov_b32_e32 v51, 0xc0135761
	s_mov_b32 s6, 0
	global_load_ushort v60, v0, s[10:11] offset:0
	global_load_ushort v68, v0, s[12:13] offset:0
	global_load_ushort v76, v0, s[14:15] offset:0
	global_load_ushort v61, v0, s[10:11] offset:1024
	global_load_ushort v69, v0, s[12:13] offset:1024
	global_load_ushort v77, v0, s[14:15] offset:1024
	global_load_ushort v62, v0, s[10:11] offset:2048
	global_load_ushort v70, v0, s[12:13] offset:2048
	global_load_ushort v78, v0, s[14:15] offset:2048
	global_load_ushort v63, v0, s[10:11] offset:3072
	global_load_ushort v71, v0, s[12:13] offset:3072
	global_load_ushort v79, v0, s[14:15] offset:3072
	global_load_ushort v64, v1, s[10:11] offset:0
	global_load_ushort v72, v1, s[12:13] offset:0
	global_load_ushort v80, v1, s[14:15] offset:0
	global_load_ushort v65, v1, s[10:11] offset:1024
	global_load_ushort v73, v1, s[12:13] offset:1024
	global_load_ushort v81, v1, s[14:15] offset:1024
	global_load_ushort v66, v1, s[10:11] offset:2048
	global_load_ushort v74, v1, s[12:13] offset:2048
	global_load_ushort v82, v1, s[14:15] offset:2048
	global_load_ushort v67, v1, s[10:11] offset:3072
	global_load_ushort v75, v1, s[12:13] offset:3072
	global_load_ushort v83, v1, s[14:15] offset:3072
	v_add_u32_e32 v0, 0x2000, v0
	v_add_u32_e32 v1, 0x2000, v1
.Lrg_p2:
	global_load_ushort v84, v0, s[10:11] offset:0
	global_load_ushort v92, v0, s[12:13] offset:0
	global_load_ushort v100, v0, s[14:15] offset:0
	global_load_ushort v85, v0, s[10:11] offset:1024
	global_load_ushort v93, v0, s[12:13] offset:1024
	global_load_ushort v101, v0, s[14:15] offset:1024
	global_load_ushort v86, v0, s[10:11] offset:2048
	global_load_ushort v94, v0, s[12:13] offset:2048
	global_load_ushort v102, v0, s[14:15] offset:2048
	global_load_ushort v87, v0, s[10:11] offset:3072
	global_load_ushort v95, v0, s[12:13] offset:3072
	global_load_ushort v103, v0, s[14:15] offset:3072
	global_load_ushort v88, v1, s[10:11] offset:0
	global_load_ushort v96, v1, s[12:13] offset:0
	global_load_ushort v104, v1, s[14:15] offset:0
	global_load_ushort v89, v1, s[10:11] offset:1024
	global_load_ushort v97, v1, s[12:13] offset:1024
	global_load_ushort v105, v1, s[14:15] offset:1024
	global_load_ushort v90, v1, s[10:11] offset:2048
	global_load_ushort v98, v1, s[12:13] offset:2048
	global_load_ushort v106, v1, s[14:15] offset:2048
	global_load_ushort v91, v1, s[10:11] offset:3072
	global_load_ushort v99, v1, s[12:13] offset:3072
	global_load_ushort v107, v1, s[14:15] offset:3072
	v_add_u32_e32 v0, 0x2000, v0
	v_add_u32_e32 v1, 0x2000, v1
	s_waitcnt vmcnt(24)
	v_lshlrev_b32_e32 v8, 16, v60
	v_mul_f32_e32 v8, 0x3fb8aa3b, v8
	v_lshlrev_b32_e32 v24, 16, v76
	v_lshlrev_b32_e32 v9, 16, v61
	v_mul_f32_e32 v9, 0x3fb8aa3b, v9
	v_lshlrev_b32_e32 v25, 16, v77
	v_lshlrev_b32_e32 v10, 16, v62
	v_mul_f32_e32 v10, 0x3fb8aa3b, v10
	v_lshlrev_b32_e32 v26, 16, v78
	v_lshlrev_b32_e32 v11, 16, v63
	v_mul_f32_e32 v11, 0x3fb8aa3b, v11
	v_lshlrev_b32_e32 v27, 16, v79
	v_lshlrev_b32_e32 v12, 16, v64
	v_mul_f32_e32 v12, 0x3fb8aa3b, v12
	v_lshlrev_b32_e32 v28, 16, v80
	v_lshlrev_b32_e32 v13, 16, v65
	v_mul_f32_e32 v13, 0x3fb8aa3b, v13
	v_lshlrev_b32_e32 v29, 16, v81
	v_lshlrev_b32_e32 v14, 16, v66
	v_mul_f32_e32 v14, 0x3fb8aa3b, v14
	v_lshlrev_b32_e32 v30, 16, v82
	v_lshlrev_b32_e32 v15, 16, v67
	v_mul_f32_e32 v15, 0x3fb8aa3b, v15
	v_lshlrev_b32_e32 v31, 16, v83
	v_exp_f32_e32 v8, v8
	v_mul_f32_e32 v108, v24, v24
	v_exp_f32_e32 v9, v9
	v_mul_f32_e32 v109, v25, v25
	v_exp_f32_e32 v10, v10
	v_mul_f32_e32 v110, v26, v26
	v_exp_f32_e32 v11, v11
	v_mul_f32_e32 v111, v27, v27
	v_exp_f32_e32 v12, v12
	v_mul_f32_e32 v112, v28, v28
	v_exp_f32_e32 v13, v13
	v_mul_f32_e32 v113, v29, v29
	v_exp_f32_e32 v14, v14
	v_mul_f32_e32 v114, v30, v30
	v_exp_f32_e32 v15, v15
	v_mul_f32_e32 v115, v31, v31
	v_lshlrev_b32_e32 v16, 16, v68
	v_fma_f32 v108, v108, v50, v51
	v_lshlrev_b32_e32 v17, 16, v69
	v_fma_f32 v109, v109, v50, v51
	v_lshlrev_b32_e32 v18, 16, v70
	v_fma_f32 v110, v110, v50, v51
	v_lshlrev_b32_e32 v19, 16, v71
	v_fma_f32 v111, v111, v50, v51
	v_lshlrev_b32_e32 v20, 16, v72
	v_fma_f32 v112, v112, v50, v51
	v_lshlrev_b32_e32 v21, 16, v73
	v_fma_f32 v113, v113, v50, v51
	v_lshlrev_b32_e32 v22, 16, v74
	v_fma_f32 v114, v114, v50, v51
	v_lshlrev_b32_e32 v23, 16, v75
	v_fma_f32 v115, v115, v50, v51
	v_mul_f32_e32 v108, v108, v24
	v_mul_f32_e32 v109, v109, v25
	v_mul_f32_e32 v110, v110, v26
	v_mul_f32_e32 v111, v111, v27
	v_mul_f32_e32 v112, v112, v28
	v_mul_f32_e32 v113, v113, v29
	v_mul_f32_e32 v114, v114, v30
	v_mul_f32_e32 v115, v115, v31
	v_exp_f32_e32 v108, v108
	v_fma_f32 v4, v8, v4, v16
	v_mov_b32_e32 v116, v4
	v_exp_f32_e32 v109, v109
	v_fma_f32 v4, v9, v4, v17
	v_mov_b32_e32 v117, v4
	v_exp_f32_e32 v110, v110
	v_fma_f32 v4, v10, v4, v18
	v_mov_b32_e32 v118, v4
	v_exp_f32_e32 v111, v111
	v_fma_f32 v4, v11, v4, v19
	v_mov_b32_e32 v119, v4
	v_exp_f32_e32 v112, v112
	v_fma_f32 v4, v12, v4, v20
	v_mov_b32_e32 v120, v4
	v_exp_f32_e32 v113, v113
	v_fma_f32 v4, v13, v4, v21
	v_mov_b32_e32 v121, v4
	v_exp_f32_e32 v114, v114
	v_fma_f32 v4, v14, v4, v22
	v_mov_b32_e32 v122, v4
	v_exp_f32_e32 v115, v115
	v_fma_f32 v4, v15, v4, v23
	v_mov_b32_e32 v123, v4
	v_add_f32_e32 v108, 1.0, v108
	v_add_f32_e32 v109, 1.0, v109
	v_add_f32_e32 v110, 1.0, v110
	v_add_f32_e32 v111, 1.0, v111
	v_add_f32_e32 v112, 1.0, v112
	v_add_f32_e32 v113, 1.0, v113
	v_add_f32_e32 v114, 1.0, v114
	v_add_f32_e32 v115, 1.0, v115
	v_rcp_f32_e32 v108, v108
	v_mul_f32_e32 v116, v116, v24
	v_rcp_f32_e32 v109, v109
	v_mul_f32_e32 v117, v117, v25
	v_rcp_f32_e32 v110, v110
	v_mul_f32_e32 v118, v118, v26
	v_rcp_f32_e32 v111, v111
	v_mul_f32_e32 v119, v119, v27
	v_rcp_f32_e32 v112, v112
	v_mul_f32_e32 v120, v120, v28
	v_rcp_f32_e32 v113, v113
	v_mul_f32_e32 v121, v121, v29
	v_rcp_f32_e32 v114, v114
	v_mul_f32_e32 v122, v122, v30
	v_rcp_f32_e32 v115, v115
	v_mul_f32_e32 v123, v123, v31
	v_mul_f32_e32 v116, v116, v108
	v_mul_f32_e32 v117, v117, v109
	v_mul_f32_e32 v118, v118, v110
	v_mul_f32_e32 v119, v119, v111
	v_mul_f32_e32 v120, v120, v112
	v_mul_f32_e32 v121, v121, v113
	v_mul_f32_e32 v122, v122, v114
	v_mul_f32_e32 v123, v123, v115
	v_cvt_pk_bf16_f32 v116, v116, v7
	v_cvt_pk_bf16_f32 v117, v117, v7
	v_cvt_pk_bf16_f32 v118, v118, v7
	v_cvt_pk_bf16_f32 v119, v119, v7
	v_cvt_pk_bf16_f32 v120, v120, v7
	v_cvt_pk_bf16_f32 v121, v121, v7
	v_cvt_pk_bf16_f32 v122, v122, v7
	v_cvt_pk_bf16_f32 v123, v123, v7
	global_store_short v2, v116, s[16:17] offset:0
	global_store_short v2, v117, s[16:17] offset:1024
	global_store_short v2, v118, s[16:17] offset:2048
	global_store_short v2, v119, s[16:17] offset:3072
	global_store_short v3, v120, s[16:17] offset:0
	global_store_short v3, v121, s[16:17] offset:1024
	global_store_short v3, v122, s[16:17] offset:2048
	global_store_short v3, v123, s[16:17] offset:3072
	v_add_u32_e32 v2, 0x2000, v2
	v_add_u32_e32 v3, 0x2000, v3
	s_cmp_eq_u32 s6, 30
	s_cselect_b32 s7, 0xffffe000, 0
	v_add_u32_e32 v0, s7, v0
	v_add_u32_e32 v1, s7, v1
	global_load_ushort v60, v0, s[10:11] offset:0
	global_load_ushort v68, v0, s[12:13] offset:0
	global_load_ushort v76, v0, s[14:15] offset:0
	global_load_ushort v61, v0, s[10:11] offset:1024
	global_load_ushort v69, v0, s[12:13] offset:1024
	global_load_ushort v77, v0, s[14:15] offset:1024
	global_load_ushort v62, v0, s[10:11] offset:2048
	global_load_ushort v70, v0, s[12:13] offset:2048
	global_load_ushort v78, v0, s[14:15] offset:2048
	global_load_ushort v63, v0, s[10:11] offset:3072
	global_load_ushort v71, v0, s[12:13] offset:3072
	global_load_ushort v79, v0, s[14:15] offset:3072
	global_load_ushort v64, v1, s[10:11] offset:0
	global_load_ushort v72, v1, s[12:13] offset:0
	global_load_ushort v80, v1, s[14:15] offset:0
	global_load_ushort v65, v1, s[10:11] offset:1024
	global_load_ushort v73, v1, s[12:13] offset:1024
	global_load_ushort v81, v1, s[14:15] offset:1024
	global_load_ushort v66, v1, s[10:11] offset:2048
	global_load_ushort v74, v1, s[12:13] offset:2048
	global_load_ushort v82, v1, s[14:15] offset:2048
	global_load_ushort v67, v1, s[10:11] offset:3072
	global_load_ushort v75, v1, s[12:13] offset:3072
	global_load_ushort v83, v1, s[14:15] offset:3072
	v_add_u32_e32 v0, 0x2000, v0
	v_add_u32_e32 v1, 0x2000, v1
	s_waitcnt vmcnt(32)
	v_lshlrev_b32_e32 v8, 16, v84
	v_mul_f32_e32 v8, 0x3fb8aa3b, v8
	v_lshlrev_b32_e32 v24, 16, v100
	v_lshlrev_b32_e32 v9, 16, v85
	v_mul_f32_e32 v9, 0x3fb8aa3b, v9
	v_lshlrev_b32_e32 v25, 16, v101
	v_lshlrev_b32_e32 v10, 16, v86
	v_mul_f32_e32 v10, 0x3fb8aa3b, v10
	v_lshlrev_b32_e32 v26, 16, v102
	v_lshlrev_b32_e32 v11, 16, v87
	v_mul_f32_e32 v11, 0x3fb8aa3b, v11
	v_lshlrev_b32_e32 v27, 16, v103
	v_lshlrev_b32_e32 v12, 16, v88
	v_mul_f32_e32 v12, 0x3fb8aa3b, v12
	v_lshlrev_b32_e32 v28, 16, v104
	v_lshlrev_b32_e32 v13, 16, v89
	v_mul_f32_e32 v13, 0x3fb8aa3b, v13
	v_lshlrev_b32_e32 v29, 16, v105
	v_lshlrev_b32_e32 v14, 16, v90
	v_mul_f32_e32 v14, 0x3fb8aa3b, v14
	v_lshlrev_b32_e32 v30, 16, v106
	v_lshlrev_b32_e32 v15, 16, v91
	v_mul_f32_e32 v15, 0x3fb8aa3b, v15
	v_lshlrev_b32_e32 v31, 16, v107
	v_exp_f32_e32 v8, v8
	v_mul_f32_e32 v108, v24, v24
	v_exp_f32_e32 v9, v9
	v_mul_f32_e32 v109, v25, v25
	v_exp_f32_e32 v10, v10
	v_mul_f32_e32 v110, v26, v26
	v_exp_f32_e32 v11, v11
	v_mul_f32_e32 v111, v27, v27
	v_exp_f32_e32 v12, v12
	v_mul_f32_e32 v112, v28, v28
	v_exp_f32_e32 v13, v13
	v_mul_f32_e32 v113, v29, v29
	v_exp_f32_e32 v14, v14
	v_mul_f32_e32 v114, v30, v30
	v_exp_f32_e32 v15, v15
	v_mul_f32_e32 v115, v31, v31
	v_lshlrev_b32_e32 v16, 16, v92
	v_fma_f32 v108, v108, v50, v51
	v_lshlrev_b32_e32 v17, 16, v93
	v_fma_f32 v109, v109, v50, v51
	v_lshlrev_b32_e32 v18, 16, v94
	v_fma_f32 v110, v110, v50, v51
	v_lshlrev_b32_e32 v19, 16, v95
	v_fma_f32 v111, v111, v50, v51
	v_lshlrev_b32_e32 v20, 16, v96
	v_fma_f32 v112, v112, v50, v51
	v_lshlrev_b32_e32 v21, 16, v97
	v_fma_f32 v113, v113, v50, v51
	v_lshlrev_b32_e32 v22, 16, v98
	v_fma_f32 v114, v114, v50, v51
	v_lshlrev_b32_e32 v23, 16, v99
	v_fma_f32 v115, v115, v50, v51
	v_mul_f32_e32 v108, v108, v24
	v_mul_f32_e32 v109, v109, v25
	v_mul_f32_e32 v110, v110, v26
	v_mul_f32_e32 v111, v111, v27
	v_mul_f32_e32 v112, v112, v28
	v_mul_f32_e32 v113, v113, v29
	v_mul_f32_e32 v114, v114, v30
	v_mul_f32_e32 v115, v115, v31
	v_exp_f32_e32 v108, v108
	v_fma_f32 v4, v8, v4, v16
	v_mov_b32_e32 v116, v4
	v_exp_f32_e32 v109, v109
	v_fma_f32 v4, v9, v4, v17
	v_mov_b32_e32 v117, v4
	v_exp_f32_e32 v110, v110
	v_fma_f32 v4, v10, v4, v18
	v_mov_b32_e32 v118, v4
	v_exp_f32_e32 v111, v111
	v_fma_f32 v4, v11, v4, v19
	v_mov_b32_e32 v119, v4
	v_exp_f32_e32 v112, v112
	v_fma_f32 v4, v12, v4, v20
	v_mov_b32_e32 v120, v4
	v_exp_f32_e32 v113, v113
	v_fma_f32 v4, v13, v4, v21
	v_mov_b32_e32 v121, v4
	v_exp_f32_e32 v114, v114
	v_fma_f32 v4, v14, v4, v22
	v_mov_b32_e32 v122, v4
	v_exp_f32_e32 v115, v115
	v_fma_f32 v4, v15, v4, v23
	v_mov_b32_e32 v123, v4
	v_add_f32_e32 v108, 1.0, v108
	v_add_f32_e32 v109, 1.0, v109
	v_add_f32_e32 v110, 1.0, v110
	v_add_f32_e32 v111, 1.0, v111
	v_add_f32_e32 v112, 1.0, v112
	v_add_f32_e32 v113, 1.0, v113
	v_add_f32_e32 v114, 1.0, v114
	v_add_f32_e32 v115, 1.0, v115
	v_rcp_f32_e32 v108, v108
	v_mul_f32_e32 v116, v116, v24
	v_rcp_f32_e32 v109, v109
	v_mul_f32_e32 v117, v117, v25
	v_rcp_f32_e32 v110, v110
	v_mul_f32_e32 v118, v118, v26
	v_rcp_f32_e32 v111, v111
	v_mul_f32_e32 v119, v119, v27
	v_rcp_f32_e32 v112, v112
	v_mul_f32_e32 v120, v120, v28
	v_rcp_f32_e32 v113, v113
	v_mul_f32_e32 v121, v121, v29
	v_rcp_f32_e32 v114, v114
	v_mul_f32_e32 v122, v122, v30
	v_rcp_f32_e32 v115, v115
	v_mul_f32_e32 v123, v123, v31
	v_mul_f32_e32 v116, v116, v108
	v_mul_f32_e32 v117, v117, v109
	v_mul_f32_e32 v118, v118, v110
	v_mul_f32_e32 v119, v119, v111
	v_mul_f32_e32 v120, v120, v112
	v_mul_f32_e32 v121, v121, v113
	v_mul_f32_e32 v122, v122, v114
	v_mul_f32_e32 v123, v123, v115
	v_cvt_pk_bf16_f32 v116, v116, v7
	v_cvt_pk_bf16_f32 v117, v117, v7
	v_cvt_pk_bf16_f32 v118, v118, v7
	v_cvt_pk_bf16_f32 v119, v119, v7
	v_cvt_pk_bf16_f32 v120, v120, v7
	v_cvt_pk_bf16_f32 v121, v121, v7
	v_cvt_pk_bf16_f32 v122, v122, v7
	v_cvt_pk_bf16_f32 v123, v123, v7
	global_store_short v2, v116, s[16:17] offset:0
	global_store_short v2, v117, s[16:17] offset:1024
	global_store_short v2, v118, s[16:17] offset:2048
	global_store_short v2, v119, s[16:17] offset:3072
	global_store_short v3, v120, s[16:17] offset:0
	global_store_short v3, v121, s[16:17] offset:1024
	global_store_short v3, v122, s[16:17] offset:2048
	global_store_short v3, v123, s[16:17] offset:3072
	v_add_u32_e32 v2, 0x2000, v2
	v_add_u32_e32 v3, 0x2000, v3
	s_add_i32 s6, s6, 2
	s_cmp_lt_u32 s6, 32
	s_cbranch_scc1 .Lrg_p2
	s_waitcnt vmcnt(0)
	s_mov_b64 s[4:5], -1
	s_and_b64 vcc, exec, s[8:9]
	s_cbranch_vccz .LBB0_916
	s_and_b32 s6, s91, 7
	s_lshl_b32 s7, s6, 6
	v_add_u32_e32 v0, s7, v32
	v_ashrrev_i32_e32 v1, 31, v0
	v_lshlrev_b64 v[2:3], 2, v[0:1]
	v_add_u32_e32 v6, 0x200, v0
	v_add_u32_e32 v0, 0x400, v0
	v_ashrrev_i32_e32 v1, 31, v0
	v_readlane_b32 s52, v255, 7
	v_lshl_add_u64 v[4:5], s[46:47], 0, v[2:3]
	v_ashrrev_i32_e32 v7, 31, v6
	v_lshl_add_u64 v[0:1], v[0:1], 2, s[46:47]
	v_readlane_b32 s58, v255, 13
	v_readlane_b32 s59, v255, 14
	v_lshl_add_u64 v[6:7], v[6:7], 2, s[46:47]
	global_load_dword v60, v[4:5], off
	global_load_dword v61, v[6:7], off
	global_load_dword v62, v[0:1], off
	v_readlane_b32 s60, v255, 15
	v_readlane_b32 s61, v255, 16
	v_lshl_add_u64 v[0:1], s[58:59], 0, v[2:3]
	v_readlane_b32 s62, v255, 17
	v_readlane_b32 s63, v255, 18
	global_load_dword v63, v[0:1], off
	v_lshl_add_u64 v[0:1], s[60:61], 0, v[2:3]
	global_load_dword v64, v[0:1], off
	v_lshl_add_u64 v[0:1], s[62:63], 0, v[2:3]
	global_load_dword v65, v[0:1], off
	s_lshl_b32 s4, s91, 8
	v_readlane_b32 s53, v255, 8
	s_and_b32 s52, s4, 0xfffff800
	s_ashr_i32 s53, s52, 31
	s_lshl_b64 s[4:5], s[52:53], 9
	s_or_b32 s4, s4, s7
	v_lshl_add_u64 v[0:1], s[4:5], 0, v[32:33]
	v_lshlrev_b64 v[2:3], 1, v[0:1]
	v_lshl_add_u64 v[42:43], s[10:11], 0, v[2:3]
	v_lshl_add_u64 v[44:45], s[14:15], 0, v[2:3]
	v_lshl_add_u64 v[46:47], s[12:13], 0, v[2:3]
	s_waitcnt vmcnt(0)
	v_mov_b32_e32 v109, 0
	v_cmp_ne_u32_e64 s[4:5], 1, v57
	s_andn2_b64 vcc, exec, s[18:19]
	v_mov_b32_e32 v106, 0
	v_mov_b32_e32 v105, 0
	v_mov_b32_e32 v102, 0
	v_mov_b32_e32 v98, 0
	v_mov_b32_e32 v95, 0
	v_mov_b32_e32 v93, 0
	v_mov_b32_e32 v90, 0
	v_mov_b32_e32 v87, 0
	v_mov_b32_e32 v84, 0
	v_mov_b32_e32 v81, 0
	v_mov_b32_e32 v78, 0
	v_mov_b32_e32 v72, 0
	v_mov_b32_e32 v70, 0
	v_mov_b32_e32 v68, 0
	v_mov_b32_e32 v67, 0
	v_mov_b32_e32 v66, 0
	v_mov_b32_e32 v69, 0
	v_mov_b32_e32 v71, 0
	v_mov_b32_e32 v74, 0
	v_mov_b32_e32 v79, 0
	v_mov_b32_e32 v82, 0
	v_mov_b32_e32 v85, 0
	v_mov_b32_e32 v88, 0
	v_mov_b32_e32 v91, 0
	v_mov_b32_e32 v94, 0
	v_mov_b32_e32 v97, 0
	v_mov_b32_e32 v100, 0
	v_mov_b32_e32 v103, 0
	v_mov_b32_e32 v107, 0
	v_mov_b32_e32 v110, 0
	v_mov_b32_e32 v111, 0
	v_mov_b32_e32 v73, 0
	v_mov_b32_e32 v75, 0
	v_mov_b32_e32 v76, 0
	v_mov_b32_e32 v77, 0
	v_mov_b32_e32 v80, 0
	v_mov_b32_e32 v83, 0
	v_mov_b32_e32 v86, 0
	v_mov_b32_e32 v89, 0
	v_mov_b32_e32 v92, 0
	v_mov_b32_e32 v96, 0
	v_mov_b32_e32 v99, 0
	v_mov_b32_e32 v101, 0
	v_mov_b32_e32 v104, 0
	v_mov_b32_e32 v108, 0
	v_mov_b32_e32 v112, 0
	v_mov_b32_e32 v113, 0
	v_readlane_b32 s54, v255, 9
	v_readlane_b32 s55, v255, 10
	v_readlane_b32 s56, v255, 11
	v_readlane_b32 s57, v255, 12
	v_readlane_b32 s64, v255, 19
	v_readlane_b32 s65, v255, 20
	v_readlane_b32 s66, v255, 21
	v_readlane_b32 s67, v255, 22
	s_cbranch_vccnz .LBB0_875
	v_add_co_u32_e32 v2, vcc, 0x1000, v42
	global_load_ushort v73, v[42:43], off
	global_load_ushort v66, v[46:47], off
	global_load_ushort v67, v[44:45], off
	global_load_ushort v75, v[42:43], off offset:1024
	global_load_ushort v69, v[46:47], off offset:1024
	global_load_ushort v68, v[44:45], off offset:1024
	global_load_ushort v76, v[42:43], off offset:2048
	global_load_ushort v71, v[46:47], off offset:2048
	global_load_ushort v70, v[44:45], off offset:2048
	global_load_ushort v77, v[42:43], off offset:3072
	global_load_ushort v74, v[46:47], off offset:3072
	global_load_ushort v72, v[44:45], off offset:3072
	v_addc_co_u32_e32 v3, vcc, 0, v43, vcc
	v_add_co_u32_e32 v4, vcc, 0x1000, v46
	global_load_ushort v80, v[2:3], off
	s_nop 0
	v_addc_co_u32_e32 v5, vcc, 0, v47, vcc
	v_add_co_u32_e32 v6, vcc, 0x1000, v44
	global_load_ushort v79, v[4:5], off
	s_nop 0
	v_addc_co_u32_e32 v7, vcc, 0, v45, vcc
	global_load_ushort v78, v[6:7], off
	global_load_ushort v83, v[2:3], off offset:1024
	global_load_ushort v82, v[4:5], off offset:1024
	global_load_ushort v81, v[6:7], off offset:1024
	global_load_ushort v86, v[2:3], off offset:2048
	global_load_ushort v85, v[4:5], off offset:2048
	global_load_ushort v84, v[6:7], off offset:2048
	global_load_ushort v89, v[2:3], off offset:3072
	global_load_ushort v88, v[4:5], off offset:3072
	global_load_ushort v87, v[6:7], off offset:3072
	v_add_co_u32_e32 v2, vcc, 0x2000, v42
	s_nop 1
	v_addc_co_u32_e32 v3, vcc, 0, v43, vcc
	v_add_co_u32_e32 v4, vcc, 0x2000, v46
	global_load_ushort v92, v[2:3], off
	s_nop 0
	v_addc_co_u32_e32 v5, vcc, 0, v47, vcc
	v_add_co_u32_e32 v6, vcc, 0x2000, v44
	global_load_ushort v91, v[4:5], off
	s_nop 0
	v_addc_co_u32_e32 v7, vcc, 0, v45, vcc
	global_load_ushort v90, v[6:7], off
	global_load_ushort v96, v[2:3], off offset:1024
	global_load_ushort v94, v[4:5], off offset:1024
	global_load_ushort v93, v[6:7], off offset:1024
	global_load_ushort v99, v[2:3], off offset:2048
	global_load_ushort v97, v[4:5], off offset:2048
	global_load_ushort v95, v[6:7], off offset:2048
	global_load_ushort v101, v[2:3], off offset:3072
	global_load_ushort v100, v[4:5], off offset:3072
	global_load_ushort v98, v[6:7], off offset:3072
	v_add_co_u32_e32 v2, vcc, s75, v42
	s_nop 1
	v_addc_co_u32_e32 v3, vcc, 0, v43, vcc
	v_add_co_u32_e32 v4, vcc, s75, v46
	global_load_ushort v104, v[2:3], off
	s_nop 0
	v_addc_co_u32_e32 v5, vcc, 0, v47, vcc
	v_add_co_u32_e32 v6, vcc, 0x3000, v44
	global_load_ushort v103, v[4:5], off
	s_nop 0
	v_addc_co_u32_e32 v7, vcc, 0, v45, vcc
	global_load_ushort v102, v[6:7], off
	global_load_ushort v108, v[2:3], off offset:1024
	global_load_ushort v107, v[4:5], off offset:1024
	global_load_ushort v105, v[6:7], off offset:1024
	global_load_ushort v112, v[2:3], off offset:2048
	global_load_ushort v110, v[4:5], off offset:2048
	global_load_ushort v106, v[6:7], off offset:2048
	global_load_ushort v113, v[2:3], off offset:3072
	global_load_ushort v111, v[4:5], off offset:3072
	global_load_ushort v109, v[6:7], off offset:3072

.LBB0_916:
	s_and_b64 vcc, exec, s[4:5]
	s_cbranch_vccz .LBB0_871
	s_and_b32 s4, s83, 0xfffff800
	s_ashr_i32 s5, s4, 31
	s_and_b32 s6, s90, 7
	s_lshl_b64 s[4:5], s[4:5], 10
	s_lshl_b32 s6, s6, 7
	s_waitcnt lgkmcnt(0)
	s_barrier
	s_or_b32 s4, s4, s6
	v_lshl_add_u64 v[0:1], v[40:41], 0, s[4:5]
	v_mov_b32_e32 v4, 0
	s_mov_b32 s6, 0
	v_mov_b32_e32 v5, 0
	v_mov_b32_e32 v6, 0
	v_mov_b32_e32 v7, 0
	v_mov_b32_e32 v8, 0
	v_mov_b32_e32 v9, 0
	v_mov_b32_e32 v10, 0
	v_mov_b32_e32 v11, 0
	s_waitcnt vmcnt(0)
	v_mov_b32_e32 v12, 0
	v_mov_b32_e32 v13, 0
	v_mov_b32_e32 v14, 0
	v_mov_b32_e32 v15, 0
	v_mov_b32_e32 v16, 0
	v_mov_b32_e32 v17, 0
	v_mov_b32_e32 v18, 0
	v_mov_b32_e32 v19, 0
	s_add_u32 s4, s4, s96
	s_addc_u32 s5, s5, s97
	s_add_u32 s4, s4, 0x1d800000
	s_addc_u32 s5, s5, 0
	v_add_u32_e32 v52, 0xfffffb00, v38
	v_lshrrev_b32_e32 v52, 1, v52
	v_lshrrev_b32_e32 v53, 4, v32
	v_and_b32_e32 v54, 1, v53
	v_lshrrev_b32_e32 v53, 1, v53
	v_lshl_or_b32 v53, v54, 1, v53
	v_lshl_add_u32 v52, v53, 10, v52
	s_setprio 2
.Lsc_blk:
	s_bitcmp1_b32 s6, 0
	s_cselect_b32 s7, 0xc000, 0
	v_add_u32_e32 v2, s7, v38
	v_add_u32_e32 v3, s7, v56
	s_mov_b32 s7, 0
	s_nop 0
	ds_read2st64_b32 v[20:21], v3 offset0:0 offset1:1
	ds_read2st64_b32 v[22:23], v3 offset0:2 offset1:3
	ds_read_b32 v24, v3 offset:1024
	ds_read_b32 v25, v2 offset:0
.Lsc_it:
	s_waitcnt lgkmcnt(0)
	ds_read2st64_b32 v[26:27], v3 offset0:6 offset1:7
	ds_read2st64_b32 v[28:29], v3 offset0:8 offset1:9
	ds_read_b32 v30, v3 offset:2560
	ds_read_b32 v31, v2 offset:1536
	v_mul_f32_dpp v0, v20, v4 row_newbcast:0 row_mask:0xf bank_mask:0xf
	v_mul_f32_dpp v1, v20, v5 row_newbcast:1 row_mask:0xf bank_mask:0xf
	v_mul_f32_dpp v4, v23, v4 row_newbcast:0 row_mask:0xf bank_mask:0xf
	v_fmac_f32_dpp v0, v20, v6 row_newbcast:2 row_mask:0xf bank_mask:0xf
	v_mul_f32_dpp v5, v23, v5 row_newbcast:1 row_mask:0xf bank_mask:0xf
	v_fmac_f32_dpp v1, v20, v7 row_newbcast:3 row_mask:0xf bank_mask:0xf
	v_mul_f32_dpp v6, v23, v6 row_newbcast:2 row_mask:0xf bank_mask:0xf
	v_fmac_f32_dpp v0, v20, v8 row_newbcast:4 row_mask:0xf bank_mask:0xf
	v_mul_f32_dpp v7, v23, v7 row_newbcast:3 row_mask:0xf bank_mask:0xf
	v_fmac_f32_dpp v1, v20, v9 row_newbcast:5 row_mask:0xf bank_mask:0xf
	v_mul_f32_dpp v8, v23, v8 row_newbcast:4 row_mask:0xf bank_mask:0xf
	v_fmac_f32_dpp v0, v20, v10 row_newbcast:6 row_mask:0xf bank_mask:0xf
	v_mul_f32_dpp v9, v23, v9 row_newbcast:5 row_mask:0xf bank_mask:0xf
	v_fmac_f32_dpp v1, v20, v11 row_newbcast:7 row_mask:0xf bank_mask:0xf
	v_mul_f32_dpp v10, v23, v10 row_newbcast:6 row_mask:0xf bank_mask:0xf
	v_fmac_f32_dpp v0, v20, v12 row_newbcast:8 row_mask:0xf bank_mask:0xf
	v_mul_f32_dpp v11, v23, v11 row_newbcast:7 row_mask:0xf bank_mask:0xf
	v_fmac_f32_dpp v1, v20, v13 row_newbcast:9 row_mask:0xf bank_mask:0xf
	v_mul_f32_dpp v12, v23, v12 row_newbcast:8 row_mask:0xf bank_mask:0xf
	v_fmac_f32_dpp v0, v20, v14 row_newbcast:10 row_mask:0xf bank_mask:0xf
	v_mul_f32_dpp v13, v23, v13 row_newbcast:9 row_mask:0xf bank_mask:0xf
	v_fmac_f32_dpp v1, v20, v15 row_newbcast:11 row_mask:0xf bank_mask:0xf
	v_mul_f32_dpp v14, v23, v14 row_newbcast:10 row_mask:0xf bank_mask:0xf
	v_fmac_f32_dpp v0, v20, v16 row_newbcast:12 row_mask:0xf bank_mask:0xf
	v_mul_f32_dpp v15, v23, v15 row_newbcast:11 row_mask:0xf bank_mask:0xf
	v_fmac_f32_dpp v1, v20, v17 row_newbcast:13 row_mask:0xf bank_mask:0xf
	v_mul_f32_dpp v16, v23, v16 row_newbcast:12 row_mask:0xf bank_mask:0xf
	v_fmac_f32_dpp v0, v20, v18 row_newbcast:14 row_mask:0xf bank_mask:0xf
	v_mul_f32_dpp v17, v23, v17 row_newbcast:13 row_mask:0xf bank_mask:0xf
	v_fmac_f32_dpp v1, v20, v19 row_newbcast:15 row_mask:0xf bank_mask:0xf
	v_mul_f32_dpp v18, v23, v18 row_newbcast:14 row_mask:0xf bank_mask:0xf
	v_mul_f32_dpp v19, v23, v19 row_newbcast:15 row_mask:0xf bank_mask:0xf
	v_fmac_f32_dpp v4, v22, v25 row_newbcast:0 row_mask:0xf bank_mask:0xf
	v_fmac_f32_dpp v5, v22, v25 row_newbcast:1 row_mask:0xf bank_mask:0xf
	v_add_f32_e32 v46, v0, v1
	v_add_f32_e32 v47, v0, v1
	v_fmac_f32_dpp v6, v22, v25 row_newbcast:2 row_mask:0xf bank_mask:0xf
	v_fmac_f32_dpp v7, v22, v25 row_newbcast:3 row_mask:0xf bank_mask:0xf
	v_permlane32_swap_b32_e32 v46, v47
	v_fmac_f32_dpp v8, v22, v25 row_newbcast:4 row_mask:0xf bank_mask:0xf
	v_fmac_f32_dpp v9, v22, v25 row_newbcast:5 row_mask:0xf bank_mask:0xf
	v_add_f32_e32 v48, v46, v47
	v_add_f32_e32 v49, v46, v47
	v_fmac_f32_dpp v10, v22, v25 row_newbcast:6 row_mask:0xf bank_mask:0xf
	v_fmac_f32_dpp v11, v22, v25 row_newbcast:7 row_mask:0xf bank_mask:0xf
	v_permlane16_swap_b32_e32 v48, v49
	v_fmac_f32_dpp v12, v22, v25 row_newbcast:8 row_mask:0xf bank_mask:0xf
	v_fmac_f32_dpp v13, v22, v25 row_newbcast:9 row_mask:0xf bank_mask:0xf
	v_add_f32_e32 v50, v48, v49
	v_fmac_f32_dpp v14, v22, v25 row_newbcast:10 row_mask:0xf bank_mask:0xf
	v_fmac_f32_dpp v15, v22, v25 row_newbcast:11 row_mask:0xf bank_mask:0xf
	v_fmac_f32_dpp v16, v22, v25 row_newbcast:12 row_mask:0xf bank_mask:0xf
	v_fmac_f32_dpp v17, v22, v25 row_newbcast:13 row_mask:0xf bank_mask:0xf
	v_fmac_f32_dpp v18, v22, v25 row_newbcast:14 row_mask:0xf bank_mask:0xf
	v_fmac_f32_dpp v19, v22, v25 row_newbcast:15 row_mask:0xf bank_mask:0xf
	v_fmac_f32_dpp v4, v21, v50 row_newbcast:0 row_mask:0xf bank_mask:0xf
	v_fmac_f32_dpp v5, v21, v50 row_newbcast:1 row_mask:0xf bank_mask:0xf
	v_fmac_f32_dpp v6, v21, v50 row_newbcast:2 row_mask:0xf bank_mask:0xf
	v_mul_f32_dpp v60, v24, v4 row_newbcast:0 row_mask:0xf bank_mask:0xf
	v_fmac_f32_dpp v7, v21, v50 row_newbcast:3 row_mask:0xf bank_mask:0xf
	v_mul_f32_dpp v61, v24, v5 row_newbcast:1 row_mask:0xf bank_mask:0xf
	v_fmac_f32_dpp v8, v21, v50 row_newbcast:4 row_mask:0xf bank_mask:0xf
	v_fmac_f32_dpp v60, v24, v6 row_newbcast:2 row_mask:0xf bank_mask:0xf
	v_fmac_f32_dpp v9, v21, v50 row_newbcast:5 row_mask:0xf bank_mask:0xf
	v_fmac_f32_dpp v61, v24, v7 row_newbcast:3 row_mask:0xf bank_mask:0xf
	v_fmac_f32_dpp v10, v21, v50 row_newbcast:6 row_mask:0xf bank_mask:0xf
	v_fmac_f32_dpp v60, v24, v8 row_newbcast:4 row_mask:0xf bank_mask:0xf
	v_fmac_f32_dpp v11, v21, v50 row_newbcast:7 row_mask:0xf bank_mask:0xf
	v_fmac_f32_dpp v61, v24, v9 row_newbcast:5 row_mask:0xf bank_mask:0xf
	v_fmac_f32_dpp v12, v21, v50 row_newbcast:8 row_mask:0xf bank_mask:0xf
	v_fmac_f32_dpp v60, v24, v10 row_newbcast:6 row_mask:0xf bank_mask:0xf
	v_fmac_f32_dpp v13, v21, v50 row_newbcast:9 row_mask:0xf bank_mask:0xf
	v_fmac_f32_dpp v61, v24, v11 row_newbcast:7 row_mask:0xf bank_mask:0xf
	v_fmac_f32_dpp v14, v21, v50 row_newbcast:10 row_mask:0xf bank_mask:0xf
	v_fmac_f32_dpp v60, v24, v12 row_newbcast:8 row_mask:0xf bank_mask:0xf
	v_fmac_f32_dpp v15, v21, v50 row_newbcast:11 row_mask:0xf bank_mask:0xf
	v_fmac_f32_dpp v61, v24, v13 row_newbcast:9 row_mask:0xf bank_mask:0xf
	v_fmac_f32_dpp v16, v21, v50 row_newbcast:12 row_mask:0xf bank_mask:0xf
	v_fmac_f32_dpp v60, v24, v14 row_newbcast:10 row_mask:0xf bank_mask:0xf
	v_fmac_f32_dpp v17, v21, v50 row_newbcast:13 row_mask:0xf bank_mask:0xf
	v_fmac_f32_dpp v61, v24, v15 row_newbcast:11 row_mask:0xf bank_mask:0xf
	v_fmac_f32_dpp v18, v21, v50 row_newbcast:14 row_mask:0xf bank_mask:0xf
	v_fmac_f32_dpp v60, v24, v16 row_newbcast:12 row_mask:0xf bank_mask:0xf
	v_fmac_f32_dpp v19, v21, v50 row_newbcast:15 row_mask:0xf bank_mask:0xf
	v_fmac_f32_dpp v61, v24, v17 row_newbcast:13 row_mask:0xf bank_mask:0xf
	v_fmac_f32_dpp v60, v24, v18 row_newbcast:14 row_mask:0xf bank_mask:0xf
	v_fmac_f32_dpp v61, v24, v19 row_newbcast:15 row_mask:0xf bank_mask:0xf
	s_waitcnt lgkmcnt(0)
	ds_read2st64_b32 v[20:21], v3 offset0:12 offset1:13
	ds_read2st64_b32 v[22:23], v3 offset0:14 offset1:15
	ds_read_b32 v24, v3 offset:4096
	ds_read_b32 v25, v2 offset:3072
	v_mul_f32_dpp v0, v26, v4 row_newbcast:0 row_mask:0xf bank_mask:0xf
	v_mul_f32_dpp v1, v26, v5 row_newbcast:1 row_mask:0xf bank_mask:0xf
	v_mul_f32_dpp v4, v29, v4 row_newbcast:0 row_mask:0xf bank_mask:0xf
	v_fmac_f32_dpp v0, v26, v6 row_newbcast:2 row_mask:0xf bank_mask:0xf
	v_mul_f32_dpp v5, v29, v5 row_newbcast:1 row_mask:0xf bank_mask:0xf
	v_fmac_f32_dpp v1, v26, v7 row_newbcast:3 row_mask:0xf bank_mask:0xf
	v_mul_f32_dpp v6, v29, v6 row_newbcast:2 row_mask:0xf bank_mask:0xf
	v_fmac_f32_dpp v0, v26, v8 row_newbcast:4 row_mask:0xf bank_mask:0xf
	v_mul_f32_dpp v7, v29, v7 row_newbcast:3 row_mask:0xf bank_mask:0xf
	v_fmac_f32_dpp v1, v26, v9 row_newbcast:5 row_mask:0xf bank_mask:0xf
	v_mul_f32_dpp v8, v29, v8 row_newbcast:4 row_mask:0xf bank_mask:0xf
	v_fmac_f32_dpp v0, v26, v10 row_newbcast:6 row_mask:0xf bank_mask:0xf
	v_mul_f32_dpp v9, v29, v9 row_newbcast:5 row_mask:0xf bank_mask:0xf
	v_fmac_f32_dpp v1, v26, v11 row_newbcast:7 row_mask:0xf bank_mask:0xf
	v_mul_f32_dpp v10, v29, v10 row_newbcast:6 row_mask:0xf bank_mask:0xf
	v_fmac_f32_dpp v0, v26, v12 row_newbcast:8 row_mask:0xf bank_mask:0xf
	v_mul_f32_dpp v11, v29, v11 row_newbcast:7 row_mask:0xf bank_mask:0xf
	v_fmac_f32_dpp v1, v26, v13 row_newbcast:9 row_mask:0xf bank_mask:0xf
	v_mul_f32_dpp v12, v29, v12 row_newbcast:8 row_mask:0xf bank_mask:0xf
	v_fmac_f32_dpp v0, v26, v14 row_newbcast:10 row_mask:0xf bank_mask:0xf
	v_mul_f32_dpp v13, v29, v13 row_newbcast:9 row_mask:0xf bank_mask:0xf
	v_fmac_f32_dpp v1, v26, v15 row_newbcast:11 row_mask:0xf bank_mask:0xf
	v_mul_f32_dpp v14, v29, v14 row_newbcast:10 row_mask:0xf bank_mask:0xf
	v_fmac_f32_dpp v0, v26, v16 row_newbcast:12 row_mask:0xf bank_mask:0xf
	v_mul_f32_dpp v15, v29, v15 row_newbcast:11 row_mask:0xf bank_mask:0xf
	v_fmac_f32_dpp v1, v26, v17 row_newbcast:13 row_mask:0xf bank_mask:0xf
	v_mul_f32_dpp v16, v29, v16 row_newbcast:12 row_mask:0xf bank_mask:0xf
	v_fmac_f32_dpp v0, v26, v18 row_newbcast:14 row_mask:0xf bank_mask:0xf
	v_mul_f32_dpp v17, v29, v17 row_newbcast:13 row_mask:0xf bank_mask:0xf
	v_fmac_f32_dpp v1, v26, v19 row_newbcast:15 row_mask:0xf bank_mask:0xf
	v_mul_f32_dpp v18, v29, v18 row_newbcast:14 row_mask:0xf bank_mask:0xf
	v_mul_f32_dpp v19, v29, v19 row_newbcast:15 row_mask:0xf bank_mask:0xf
	v_fmac_f32_dpp v4, v28, v31 row_newbcast:0 row_mask:0xf bank_mask:0xf
	v_fmac_f32_dpp v5, v28, v31 row_newbcast:1 row_mask:0xf bank_mask:0xf
	v_add_f32_e32 v46, v0, v1
	v_add_f32_e32 v47, v0, v1
	v_fmac_f32_dpp v6, v28, v31 row_newbcast:2 row_mask:0xf bank_mask:0xf
	v_fmac_f32_dpp v7, v28, v31 row_newbcast:3 row_mask:0xf bank_mask:0xf
	v_permlane32_swap_b32_e32 v46, v47
	v_fmac_f32_dpp v8, v28, v31 row_newbcast:4 row_mask:0xf bank_mask:0xf
	v_fmac_f32_dpp v9, v28, v31 row_newbcast:5 row_mask:0xf bank_mask:0xf
	v_add_f32_e32 v48, v46, v47
	v_add_f32_e32 v49, v46, v47
	v_fmac_f32_dpp v10, v28, v31 row_newbcast:6 row_mask:0xf bank_mask:0xf
	v_fmac_f32_dpp v11, v28, v31 row_newbcast:7 row_mask:0xf bank_mask:0xf
	v_permlane16_swap_b32_e32 v48, v49
	v_fmac_f32_dpp v12, v28, v31 row_newbcast:8 row_mask:0xf bank_mask:0xf
	v_fmac_f32_dpp v13, v28, v31 row_newbcast:9 row_mask:0xf bank_mask:0xf
	v_add_f32_e32 v50, v48, v49
	v_fmac_f32_dpp v14, v28, v31 row_newbcast:10 row_mask:0xf bank_mask:0xf
	v_fmac_f32_dpp v15, v28, v31 row_newbcast:11 row_mask:0xf bank_mask:0xf
	v_fmac_f32_dpp v16, v28, v31 row_newbcast:12 row_mask:0xf bank_mask:0xf
	v_fmac_f32_dpp v17, v28, v31 row_newbcast:13 row_mask:0xf bank_mask:0xf
	v_fmac_f32_dpp v18, v28, v31 row_newbcast:14 row_mask:0xf bank_mask:0xf
	v_fmac_f32_dpp v19, v28, v31 row_newbcast:15 row_mask:0xf bank_mask:0xf
	v_fmac_f32_dpp v4, v27, v50 row_newbcast:0 row_mask:0xf bank_mask:0xf
	v_fmac_f32_dpp v5, v27, v50 row_newbcast:1 row_mask:0xf bank_mask:0xf
	v_fmac_f32_dpp v6, v27, v50 row_newbcast:2 row_mask:0xf bank_mask:0xf
	v_mul_f32_dpp v62, v30, v4 row_newbcast:0 row_mask:0xf bank_mask:0xf
	v_fmac_f32_dpp v7, v27, v50 row_newbcast:3 row_mask:0xf bank_mask:0xf
	v_mul_f32_dpp v63, v30, v5 row_newbcast:1 row_mask:0xf bank_mask:0xf
	v_fmac_f32_dpp v8, v27, v50 row_newbcast:4 row_mask:0xf bank_mask:0xf
	v_fmac_f32_dpp v62, v30, v6 row_newbcast:2 row_mask:0xf bank_mask:0xf
	v_fmac_f32_dpp v9, v27, v50 row_newbcast:5 row_mask:0xf bank_mask:0xf
	v_fmac_f32_dpp v63, v30, v7 row_newbcast:3 row_mask:0xf bank_mask:0xf
	v_fmac_f32_dpp v10, v27, v50 row_newbcast:6 row_mask:0xf bank_mask:0xf
	v_fmac_f32_dpp v62, v30, v8 row_newbcast:4 row_mask:0xf bank_mask:0xf
	v_fmac_f32_dpp v11, v27, v50 row_newbcast:7 row_mask:0xf bank_mask:0xf
	v_fmac_f32_dpp v63, v30, v9 row_newbcast:5 row_mask:0xf bank_mask:0xf
	v_fmac_f32_dpp v12, v27, v50 row_newbcast:8 row_mask:0xf bank_mask:0xf
	v_fmac_f32_dpp v62, v30, v10 row_newbcast:6 row_mask:0xf bank_mask:0xf
	v_fmac_f32_dpp v13, v27, v50 row_newbcast:9 row_mask:0xf bank_mask:0xf
	v_fmac_f32_dpp v63, v30, v11 row_newbcast:7 row_mask:0xf bank_mask:0xf
	v_fmac_f32_dpp v14, v27, v50 row_newbcast:10 row_mask:0xf bank_mask:0xf
	v_fmac_f32_dpp v62, v30, v12 row_newbcast:8 row_mask:0xf bank_mask:0xf
	v_fmac_f32_dpp v15, v27, v50 row_newbcast:11 row_mask:0xf bank_mask:0xf
	v_fmac_f32_dpp v63, v30, v13 row_newbcast:9 row_mask:0xf bank_mask:0xf
	v_fmac_f32_dpp v16, v27, v50 row_newbcast:12 row_mask:0xf bank_mask:0xf
	v_fmac_f32_dpp v62, v30, v14 row_newbcast:10 row_mask:0xf bank_mask:0xf
	v_fmac_f32_dpp v17, v27, v50 row_newbcast:13 row_mask:0xf bank_mask:0xf
	v_fmac_f32_dpp v63, v30, v15 row_newbcast:11 row_mask:0xf bank_mask:0xf
	v_fmac_f32_dpp v18, v27, v50 row_newbcast:14 row_mask:0xf bank_mask:0xf
	v_fmac_f32_dpp v62, v30, v16 row_newbcast:12 row_mask:0xf bank_mask:0xf
	v_fmac_f32_dpp v19, v27, v50 row_newbcast:15 row_mask:0xf bank_mask:0xf
	v_fmac_f32_dpp v63, v30, v17 row_newbcast:13 row_mask:0xf bank_mask:0xf
	v_fmac_f32_dpp v62, v30, v18 row_newbcast:14 row_mask:0xf bank_mask:0xf
	v_fmac_f32_dpp v63, v30, v19 row_newbcast:15 row_mask:0xf bank_mask:0xf
	s_waitcnt lgkmcnt(0)
	ds_read2st64_b32 v[26:27], v3 offset0:18 offset1:19
	ds_read2st64_b32 v[28:29], v3 offset0:20 offset1:21
	ds_read_b32 v30, v3 offset:5632
	ds_read_b32 v31, v2 offset:4608
	v_mul_f32_dpp v0, v20, v4 row_newbcast:0 row_mask:0xf bank_mask:0xf
	v_mul_f32_dpp v1, v20, v5 row_newbcast:1 row_mask:0xf bank_mask:0xf
	v_mul_f32_dpp v4, v23, v4 row_newbcast:0 row_mask:0xf bank_mask:0xf
	v_fmac_f32_dpp v0, v20, v6 row_newbcast:2 row_mask:0xf bank_mask:0xf
	v_mul_f32_dpp v5, v23, v5 row_newbcast:1 row_mask:0xf bank_mask:0xf
	v_fmac_f32_dpp v1, v20, v7 row_newbcast:3 row_mask:0xf bank_mask:0xf
	v_mul_f32_dpp v6, v23, v6 row_newbcast:2 row_mask:0xf bank_mask:0xf
	v_fmac_f32_dpp v0, v20, v8 row_newbcast:4 row_mask:0xf bank_mask:0xf
	v_mul_f32_dpp v7, v23, v7 row_newbcast:3 row_mask:0xf bank_mask:0xf
	v_fmac_f32_dpp v1, v20, v9 row_newbcast:5 row_mask:0xf bank_mask:0xf
	v_mul_f32_dpp v8, v23, v8 row_newbcast:4 row_mask:0xf bank_mask:0xf
	v_fmac_f32_dpp v0, v20, v10 row_newbcast:6 row_mask:0xf bank_mask:0xf
	v_mul_f32_dpp v9, v23, v9 row_newbcast:5 row_mask:0xf bank_mask:0xf
	v_fmac_f32_dpp v1, v20, v11 row_newbcast:7 row_mask:0xf bank_mask:0xf
	v_mul_f32_dpp v10, v23, v10 row_newbcast:6 row_mask:0xf bank_mask:0xf
	v_fmac_f32_dpp v0, v20, v12 row_newbcast:8 row_mask:0xf bank_mask:0xf
	v_mul_f32_dpp v11, v23, v11 row_newbcast:7 row_mask:0xf bank_mask:0xf
	v_fmac_f32_dpp v1, v20, v13 row_newbcast:9 row_mask:0xf bank_mask:0xf
	v_mul_f32_dpp v12, v23, v12 row_newbcast:8 row_mask:0xf bank_mask:0xf
	v_fmac_f32_dpp v0, v20, v14 row_newbcast:10 row_mask:0xf bank_mask:0xf
	v_mul_f32_dpp v13, v23, v13 row_newbcast:9 row_mask:0xf bank_mask:0xf
	v_fmac_f32_dpp v1, v20, v15 row_newbcast:11 row_mask:0xf bank_mask:0xf
	v_mul_f32_dpp v14, v23, v14 row_newbcast:10 row_mask:0xf bank_mask:0xf
	v_fmac_f32_dpp v0, v20, v16 row_newbcast:12 row_mask:0xf bank_mask:0xf
	v_mul_f32_dpp v15, v23, v15 row_newbcast:11 row_mask:0xf bank_mask:0xf
	v_fmac_f32_dpp v1, v20, v17 row_newbcast:13 row_mask:0xf bank_mask:0xf
	v_mul_f32_dpp v16, v23, v16 row_newbcast:12 row_mask:0xf bank_mask:0xf
	v_fmac_f32_dpp v0, v20, v18 row_newbcast:14 row_mask:0xf bank_mask:0xf
	v_mul_f32_dpp v17, v23, v17 row_newbcast:13 row_mask:0xf bank_mask:0xf
	v_fmac_f32_dpp v1, v20, v19 row_newbcast:15 row_mask:0xf bank_mask:0xf
	v_mul_f32_dpp v18, v23, v18 row_newbcast:14 row_mask:0xf bank_mask:0xf
	v_mul_f32_dpp v19, v23, v19 row_newbcast:15 row_mask:0xf bank_mask:0xf
	v_fmac_f32_dpp v4, v22, v25 row_newbcast:0 row_mask:0xf bank_mask:0xf
	v_fmac_f32_dpp v5, v22, v25 row_newbcast:1 row_mask:0xf bank_mask:0xf
	v_add_f32_e32 v46, v0, v1
	v_add_f32_e32 v47, v0, v1
	v_fmac_f32_dpp v6, v22, v25 row_newbcast:2 row_mask:0xf bank_mask:0xf
	v_fmac_f32_dpp v7, v22, v25 row_newbcast:3 row_mask:0xf bank_mask:0xf
	v_permlane32_swap_b32_e32 v46, v47
	v_fmac_f32_dpp v8, v22, v25 row_newbcast:4 row_mask:0xf bank_mask:0xf
	v_fmac_f32_dpp v9, v22, v25 row_newbcast:5 row_mask:0xf bank_mask:0xf
	v_add_f32_e32 v48, v46, v47
	v_add_f32_e32 v49, v46, v47
	v_fmac_f32_dpp v10, v22, v25 row_newbcast:6 row_mask:0xf bank_mask:0xf
	v_fmac_f32_dpp v11, v22, v25 row_newbcast:7 row_mask:0xf bank_mask:0xf
	v_permlane16_swap_b32_e32 v48, v49
	v_fmac_f32_dpp v12, v22, v25 row_newbcast:8 row_mask:0xf bank_mask:0xf
	v_fmac_f32_dpp v13, v22, v25 row_newbcast:9 row_mask:0xf bank_mask:0xf
	v_add_f32_e32 v50, v48, v49
	v_fmac_f32_dpp v14, v22, v25 row_newbcast:10 row_mask:0xf bank_mask:0xf
	v_fmac_f32_dpp v15, v22, v25 row_newbcast:11 row_mask:0xf bank_mask:0xf
	v_fmac_f32_dpp v16, v22, v25 row_newbcast:12 row_mask:0xf bank_mask:0xf
	v_fmac_f32_dpp v17, v22, v25 row_newbcast:13 row_mask:0xf bank_mask:0xf
	v_fmac_f32_dpp v18, v22, v25 row_newbcast:14 row_mask:0xf bank_mask:0xf
	v_fmac_f32_dpp v19, v22, v25 row_newbcast:15 row_mask:0xf bank_mask:0xf
	v_fmac_f32_dpp v4, v21, v50 row_newbcast:0 row_mask:0xf bank_mask:0xf
	v_fmac_f32_dpp v5, v21, v50 row_newbcast:1 row_mask:0xf bank_mask:0xf
	v_fmac_f32_dpp v6, v21, v50 row_newbcast:2 row_mask:0xf bank_mask:0xf
	v_mul_f32_dpp v64, v24, v4 row_newbcast:0 row_mask:0xf bank_mask:0xf
	v_fmac_f32_dpp v7, v21, v50 row_newbcast:3 row_mask:0xf bank_mask:0xf
	v_mul_f32_dpp v65, v24, v5 row_newbcast:1 row_mask:0xf bank_mask:0xf
	v_fmac_f32_dpp v8, v21, v50 row_newbcast:4 row_mask:0xf bank_mask:0xf
	v_fmac_f32_dpp v64, v24, v6 row_newbcast:2 row_mask:0xf bank_mask:0xf
	v_fmac_f32_dpp v9, v21, v50 row_newbcast:5 row_mask:0xf bank_mask:0xf
	v_fmac_f32_dpp v65, v24, v7 row_newbcast:3 row_mask:0xf bank_mask:0xf
	v_fmac_f32_dpp v10, v21, v50 row_newbcast:6 row_mask:0xf bank_mask:0xf
	v_fmac_f32_dpp v64, v24, v8 row_newbcast:4 row_mask:0xf bank_mask:0xf
	v_fmac_f32_dpp v11, v21, v50 row_newbcast:7 row_mask:0xf bank_mask:0xf
	v_fmac_f32_dpp v65, v24, v9 row_newbcast:5 row_mask:0xf bank_mask:0xf
	v_fmac_f32_dpp v12, v21, v50 row_newbcast:8 row_mask:0xf bank_mask:0xf
	v_fmac_f32_dpp v64, v24, v10 row_newbcast:6 row_mask:0xf bank_mask:0xf
	v_fmac_f32_dpp v13, v21, v50 row_newbcast:9 row_mask:0xf bank_mask:0xf
	v_fmac_f32_dpp v65, v24, v11 row_newbcast:7 row_mask:0xf bank_mask:0xf
	v_fmac_f32_dpp v14, v21, v50 row_newbcast:10 row_mask:0xf bank_mask:0xf
	v_fmac_f32_dpp v64, v24, v12 row_newbcast:8 row_mask:0xf bank_mask:0xf
	v_fmac_f32_dpp v15, v21, v50 row_newbcast:11 row_mask:0xf bank_mask:0xf
	v_fmac_f32_dpp v65, v24, v13 row_newbcast:9 row_mask:0xf bank_mask:0xf
	v_fmac_f32_dpp v16, v21, v50 row_newbcast:12 row_mask:0xf bank_mask:0xf
	v_fmac_f32_dpp v64, v24, v14 row_newbcast:10 row_mask:0xf bank_mask:0xf
	v_fmac_f32_dpp v17, v21, v50 row_newbcast:13 row_mask:0xf bank_mask:0xf
	v_fmac_f32_dpp v65, v24, v15 row_newbcast:11 row_mask:0xf bank_mask:0xf
	v_fmac_f32_dpp v18, v21, v50 row_newbcast:14 row_mask:0xf bank_mask:0xf
	v_fmac_f32_dpp v64, v24, v16 row_newbcast:12 row_mask:0xf bank_mask:0xf
	v_fmac_f32_dpp v19, v21, v50 row_newbcast:15 row_mask:0xf bank_mask:0xf
	v_fmac_f32_dpp v65, v24, v17 row_newbcast:13 row_mask:0xf bank_mask:0xf
	v_fmac_f32_dpp v64, v24, v18 row_newbcast:14 row_mask:0xf bank_mask:0xf
	v_fmac_f32_dpp v65, v24, v19 row_newbcast:15 row_mask:0xf bank_mask:0xf
	s_waitcnt lgkmcnt(0)
	ds_read2st64_b32 v[20:21], v3 offset0:24 offset1:25
	ds_read2st64_b32 v[22:23], v3 offset0:26 offset1:27
	ds_read_b32 v24, v3 offset:7168
	ds_read_b32 v25, v2 offset:6144
	v_mul_f32_dpp v0, v26, v4 row_newbcast:0 row_mask:0xf bank_mask:0xf
	v_mul_f32_dpp v1, v26, v5 row_newbcast:1 row_mask:0xf bank_mask:0xf
	v_mul_f32_dpp v4, v29, v4 row_newbcast:0 row_mask:0xf bank_mask:0xf
	v_fmac_f32_dpp v0, v26, v6 row_newbcast:2 row_mask:0xf bank_mask:0xf
	v_mul_f32_dpp v5, v29, v5 row_newbcast:1 row_mask:0xf bank_mask:0xf
	v_fmac_f32_dpp v1, v26, v7 row_newbcast:3 row_mask:0xf bank_mask:0xf
	v_mul_f32_dpp v6, v29, v6 row_newbcast:2 row_mask:0xf bank_mask:0xf
	v_fmac_f32_dpp v0, v26, v8 row_newbcast:4 row_mask:0xf bank_mask:0xf
	v_mul_f32_dpp v7, v29, v7 row_newbcast:3 row_mask:0xf bank_mask:0xf
	v_fmac_f32_dpp v1, v26, v9 row_newbcast:5 row_mask:0xf bank_mask:0xf
	v_mul_f32_dpp v8, v29, v8 row_newbcast:4 row_mask:0xf bank_mask:0xf
	v_fmac_f32_dpp v0, v26, v10 row_newbcast:6 row_mask:0xf bank_mask:0xf
	v_mul_f32_dpp v9, v29, v9 row_newbcast:5 row_mask:0xf bank_mask:0xf
	v_fmac_f32_dpp v1, v26, v11 row_newbcast:7 row_mask:0xf bank_mask:0xf
	v_mul_f32_dpp v10, v29, v10 row_newbcast:6 row_mask:0xf bank_mask:0xf
	v_fmac_f32_dpp v0, v26, v12 row_newbcast:8 row_mask:0xf bank_mask:0xf
	v_mul_f32_dpp v11, v29, v11 row_newbcast:7 row_mask:0xf bank_mask:0xf
	v_fmac_f32_dpp v1, v26, v13 row_newbcast:9 row_mask:0xf bank_mask:0xf
	v_mul_f32_dpp v12, v29, v12 row_newbcast:8 row_mask:0xf bank_mask:0xf
	v_fmac_f32_dpp v0, v26, v14 row_newbcast:10 row_mask:0xf bank_mask:0xf
	v_mul_f32_dpp v13, v29, v13 row_newbcast:9 row_mask:0xf bank_mask:0xf
	v_fmac_f32_dpp v1, v26, v15 row_newbcast:11 row_mask:0xf bank_mask:0xf
	v_mul_f32_dpp v14, v29, v14 row_newbcast:10 row_mask:0xf bank_mask:0xf
	v_fmac_f32_dpp v0, v26, v16 row_newbcast:12 row_mask:0xf bank_mask:0xf
	v_mul_f32_dpp v15, v29, v15 row_newbcast:11 row_mask:0xf bank_mask:0xf
	v_fmac_f32_dpp v1, v26, v17 row_newbcast:13 row_mask:0xf bank_mask:0xf
	v_mul_f32_dpp v16, v29, v16 row_newbcast:12 row_mask:0xf bank_mask:0xf
	v_fmac_f32_dpp v0, v26, v18 row_newbcast:14 row_mask:0xf bank_mask:0xf
	v_mul_f32_dpp v17, v29, v17 row_newbcast:13 row_mask:0xf bank_mask:0xf
	v_fmac_f32_dpp v1, v26, v19 row_newbcast:15 row_mask:0xf bank_mask:0xf
	v_mul_f32_dpp v18, v29, v18 row_newbcast:14 row_mask:0xf bank_mask:0xf
	v_mul_f32_dpp v19, v29, v19 row_newbcast:15 row_mask:0xf bank_mask:0xf
	v_fmac_f32_dpp v4, v28, v31 row_newbcast:0 row_mask:0xf bank_mask:0xf
	v_fmac_f32_dpp v5, v28, v31 row_newbcast:1 row_mask:0xf bank_mask:0xf
	v_add_f32_e32 v46, v0, v1
	v_add_f32_e32 v47, v0, v1
	v_fmac_f32_dpp v6, v28, v31 row_newbcast:2 row_mask:0xf bank_mask:0xf
	v_fmac_f32_dpp v7, v28, v31 row_newbcast:3 row_mask:0xf bank_mask:0xf
	v_permlane32_swap_b32_e32 v46, v47
	v_fmac_f32_dpp v8, v28, v31 row_newbcast:4 row_mask:0xf bank_mask:0xf
	v_fmac_f32_dpp v9, v28, v31 row_newbcast:5 row_mask:0xf bank_mask:0xf
	v_add_f32_e32 v48, v46, v47
	v_add_f32_e32 v49, v46, v47
	v_fmac_f32_dpp v10, v28, v31 row_newbcast:6 row_mask:0xf bank_mask:0xf
	v_fmac_f32_dpp v11, v28, v31 row_newbcast:7 row_mask:0xf bank_mask:0xf
	v_permlane16_swap_b32_e32 v48, v49
	v_fmac_f32_dpp v12, v28, v31 row_newbcast:8 row_mask:0xf bank_mask:0xf
	v_fmac_f32_dpp v13, v28, v31 row_newbcast:9 row_mask:0xf bank_mask:0xf
	v_add_f32_e32 v50, v48, v49
	v_fmac_f32_dpp v14, v28, v31 row_newbcast:10 row_mask:0xf bank_mask:0xf
	v_fmac_f32_dpp v15, v28, v31 row_newbcast:11 row_mask:0xf bank_mask:0xf
	v_fmac_f32_dpp v16, v28, v31 row_newbcast:12 row_mask:0xf bank_mask:0xf
	v_fmac_f32_dpp v17, v28, v31 row_newbcast:13 row_mask:0xf bank_mask:0xf
	v_fmac_f32_dpp v18, v28, v31 row_newbcast:14 row_mask:0xf bank_mask:0xf
	v_fmac_f32_dpp v19, v28, v31 row_newbcast:15 row_mask:0xf bank_mask:0xf
	v_fmac_f32_dpp v4, v27, v50 row_newbcast:0 row_mask:0xf bank_mask:0xf
	v_fmac_f32_dpp v5, v27, v50 row_newbcast:1 row_mask:0xf bank_mask:0xf
	v_fmac_f32_dpp v6, v27, v50 row_newbcast:2 row_mask:0xf bank_mask:0xf
	v_mul_f32_dpp v66, v30, v4 row_newbcast:0 row_mask:0xf bank_mask:0xf
	v_fmac_f32_dpp v7, v27, v50 row_newbcast:3 row_mask:0xf bank_mask:0xf
	v_mul_f32_dpp v67, v30, v5 row_newbcast:1 row_mask:0xf bank_mask:0xf
	v_fmac_f32_dpp v8, v27, v50 row_newbcast:4 row_mask:0xf bank_mask:0xf
	v_fmac_f32_dpp v66, v30, v6 row_newbcast:2 row_mask:0xf bank_mask:0xf
	v_fmac_f32_dpp v9, v27, v50 row_newbcast:5 row_mask:0xf bank_mask:0xf
	v_fmac_f32_dpp v67, v30, v7 row_newbcast:3 row_mask:0xf bank_mask:0xf
	v_fmac_f32_dpp v10, v27, v50 row_newbcast:6 row_mask:0xf bank_mask:0xf
	v_fmac_f32_dpp v66, v30, v8 row_newbcast:4 row_mask:0xf bank_mask:0xf
	v_fmac_f32_dpp v11, v27, v50 row_newbcast:7 row_mask:0xf bank_mask:0xf
	v_fmac_f32_dpp v67, v30, v9 row_newbcast:5 row_mask:0xf bank_mask:0xf
	v_fmac_f32_dpp v12, v27, v50 row_newbcast:8 row_mask:0xf bank_mask:0xf
	v_fmac_f32_dpp v66, v30, v10 row_newbcast:6 row_mask:0xf bank_mask:0xf
	v_fmac_f32_dpp v13, v27, v50 row_newbcast:9 row_mask:0xf bank_mask:0xf
	v_fmac_f32_dpp v67, v30, v11 row_newbcast:7 row_mask:0xf bank_mask:0xf
	v_fmac_f32_dpp v14, v27, v50 row_newbcast:10 row_mask:0xf bank_mask:0xf
	v_fmac_f32_dpp v66, v30, v12 row_newbcast:8 row_mask:0xf bank_mask:0xf
	v_fmac_f32_dpp v15, v27, v50 row_newbcast:11 row_mask:0xf bank_mask:0xf
	v_fmac_f32_dpp v67, v30, v13 row_newbcast:9 row_mask:0xf bank_mask:0xf
	v_fmac_f32_dpp v16, v27, v50 row_newbcast:12 row_mask:0xf bank_mask:0xf
	v_fmac_f32_dpp v66, v30, v14 row_newbcast:10 row_mask:0xf bank_mask:0xf
	v_fmac_f32_dpp v17, v27, v50 row_newbcast:13 row_mask:0xf bank_mask:0xf
	v_fmac_f32_dpp v67, v30, v15 row_newbcast:11 row_mask:0xf bank_mask:0xf
	v_fmac_f32_dpp v18, v27, v50 row_newbcast:14 row_mask:0xf bank_mask:0xf
	v_fmac_f32_dpp v66, v30, v16 row_newbcast:12 row_mask:0xf bank_mask:0xf
	v_fmac_f32_dpp v19, v27, v50 row_newbcast:15 row_mask:0xf bank_mask:0xf
	v_fmac_f32_dpp v67, v30, v17 row_newbcast:13 row_mask:0xf bank_mask:0xf
	v_fmac_f32_dpp v66, v30, v18 row_newbcast:14 row_mask:0xf bank_mask:0xf
	v_fmac_f32_dpp v67, v30, v19 row_newbcast:15 row_mask:0xf bank_mask:0xf
	v_add_f32_e32 v60, v60, v61
	v_add_f32_e32 v62, v62, v63
	v_add_f32_e32 v64, v64, v65
	v_add_f32_e32 v66, v66, v67
	v_add_u32_e32 v2, 0x1800, v2
	v_add_u32_e32 v3, 0x1800, v3
	v_permlane32_swap_b32_e32 v60, v62
	v_permlane32_swap_b32_e32 v64, v66
	v_add_f32_e32 v60, v60, v62
	v_add_f32_e32 v64, v64, v66
	s_add_i32 s7, s7, 1
	s_nop 1
	v_permlane16_swap_b32_e32 v60, v64
	v_add_f32_e32 v60, v60, v64
	v_cvt_pk_bf16_f32 v60, v60, v39
	global_store_short v52, v60, s[4:5]
	s_add_u32 s4, s4, 0x1000
	s_addc_u32 s5, s5, 0
	s_cmp_lt_u32 s7, 8
	s_cbranch_scc1 .Lsc_it
	s_waitcnt lgkmcnt(0)
	s_barrier
	s_add_i32 s6, s6, 1
	s_cmp_lt_u32 s6, 64
	s_cbranch_scc1 .Lsc_blk
	s_setprio 0
	s_branch .LBB0_871
